# hand-scheduled diff-attention prompt loop: softmax(j) VALU interleaved with P.V(j-1) MFMAs, bf16 P packed in place, V DMA lags one tile
# speedup vs baseline: 1.0310x; 1.0109x over previous
.LBB0_588:
	s_add_i32 s96, s11, 2
	s_cmp_lt_i32 s96, s9
	s_cbranch_scc1 .Lnl_w4e
	s_waitcnt vmcnt(0)
	s_branch .Lnl_be

.Lnl_be:
	s_barrier
	s_cmp_lt_i32 s96, s9
	s_cbranch_scc0 .Lnl_noVe
	s_cmp_lt_i32 s11, 1
	s_cbranch_scc1 .Lnl_noVe
	s_sub_u32 s6, s50, 0x60000
	s_subb_u32 s7, s51, 0
	s_add_i32 s12, s10, 0x10000
	s_and_b32 s12, s12, 0x18000
	s_add_i32 s12, s90, s12
	v_lshl_add_u64 v[2:3], s[78:79], 0, v[172:173]
	v_lshl_add_u64 v[2:3], v[2:3], 0, s[6:7]
	s_mov_b32 m0, s12
	s_nop 0
	global_load_lds_dwordx4 v[2:3], off
	v_lshl_add_u64 v[2:3], s[78:79], 0, v[170:171]
	v_lshl_add_u64 v[2:3], v[2:3], 0, s[6:7]
	s_add_i32 m0, s12, 0x2000
	s_nop 0
	global_load_lds_dwordx4 v[2:3], off
.Lnl_noVe:
	s_add_i32 s97, s11, 3
	s_cmp_lt_i32 s97, s9
	s_cbranch_scc0 .Lnl_noKe
	s_add_i32 s12, s10, 0x18000
	s_and_b32 s12, s12, 0x18000
	s_add_i32 s12, s90, s12
	v_lshl_add_u64 v[2:3], s[78:79], 0, v[168:169]
	v_lshl_add_u64 v[2:3], v[2:3], 0, s[52:53]
	s_add_i32 m0, s12, 0x4000
	s_nop 0
	global_load_lds_dwordx4 v[2:3], off
	v_lshl_add_u64 v[2:3], s[78:79], 0, v[166:167]
	v_lshl_add_u64 v[2:3], v[2:3], 0, s[52:53]
	s_add_i32 m0, s12, 0x6000
	s_nop 0
	global_load_lds_dwordx4 v[2:3], off
.Lnl_noKe:
	s_cmp_eq_u32 s11, 0
	s_cbranch_scc0 .Lnl_me
	v_max_f32_e32 v0, v81, v81
	v_max_f32_e32 v2, v80, v80
	v_max_f32_e32 v0, v2, v0
	v_max3_f32 v0, v0, v82, v83
	v_max3_f32 v0, v0, v84, v85
	v_max3_f32 v0, v0, v86, v87
	v_max3_f32 v0, v0, v88, v89
	v_max3_f32 v0, v0, v90, v91
	v_max3_f32 v0, v0, v92, v93
	v_max3_f32 v0, v0, v94, v95
	v_max3_f32 v0, v0, v96, v97
	v_max3_f32 v0, v0, v98, v99
	v_max3_f32 v0, v0, v100, v101
	v_max3_f32 v0, v0, v102, v103
	v_max3_f32 v0, v0, v104, v105
	v_max3_f32 v0, v0, v106, v107
	v_max3_f32 v0, v0, v108, v109
	v_max3_f32 v0, v0, v110, v111
	v_mov_b32_e32 v2, v0
	s_nop 1
	v_permlane32_swap_b32_e32 v0, v2
	v_max_f32_e32 v2, v2, v2
	v_max_f32_e32 v0, v0, v0
	v_max_f32_e32 v0, v0, v2
	v_sub_f32_e32 v2, v0, v193
	v_cmp_ge_f32_e64 s[0:1], s27, v2
	v_max_f32_e32 v0, v0, v0
	v_max_f32_e32 v2, v193, v193
	v_max_f32_e32 v0, v2, v0
	s_cmp_eq_u64 s[0:1], exec
	s_cselect_b64 s[0:1], -1, 0
	v_cndmask_b32_e64 v14, v0, v193, s[0:1]
	v_mul_f32_e32 v2, 0xbe38aa3b, v14
	v_fmamk_f32 v3, v80, 0x3e38aa3b, v2
	v_exp_f32_e32 v80, v3
	v_fmamk_f32 v3, v81, 0x3e38aa3b, v2
	v_exp_f32_e32 v81, v3
	v_fmamk_f32 v3, v82, 0x3e38aa3b, v2
	v_exp_f32_e32 v82, v3
	v_fmamk_f32 v3, v83, 0x3e38aa3b, v2
	v_exp_f32_e32 v83, v3
	v_fmamk_f32 v3, v84, 0x3e38aa3b, v2
	v_exp_f32_e32 v84, v3
	v_fmamk_f32 v3, v85, 0x3e38aa3b, v2
	v_exp_f32_e32 v85, v3
	v_fmamk_f32 v3, v86, 0x3e38aa3b, v2
	v_exp_f32_e32 v86, v3
	v_fmamk_f32 v3, v87, 0x3e38aa3b, v2
	v_exp_f32_e32 v87, v3
	v_fmamk_f32 v3, v88, 0x3e38aa3b, v2
	v_exp_f32_e32 v88, v3
	v_fmamk_f32 v3, v89, 0x3e38aa3b, v2
	v_exp_f32_e32 v89, v3
	v_fmamk_f32 v3, v90, 0x3e38aa3b, v2
	v_exp_f32_e32 v90, v3
	v_fmamk_f32 v3, v91, 0x3e38aa3b, v2
	v_exp_f32_e32 v91, v3
	v_fmamk_f32 v3, v92, 0x3e38aa3b, v2
	v_exp_f32_e32 v92, v3
	v_fmamk_f32 v3, v93, 0x3e38aa3b, v2
	v_exp_f32_e32 v93, v3
	v_fmamk_f32 v3, v94, 0x3e38aa3b, v2
	v_exp_f32_e32 v94, v3
	v_fmamk_f32 v3, v95, 0x3e38aa3b, v2
	v_exp_f32_e32 v95, v3
	v_fmamk_f32 v3, v96, 0x3e38aa3b, v2
	v_exp_f32_e32 v96, v3
	v_fmamk_f32 v3, v97, 0x3e38aa3b, v2
	v_exp_f32_e32 v97, v3
	v_fmamk_f32 v3, v98, 0x3e38aa3b, v2
	v_exp_f32_e32 v98, v3
	v_fmamk_f32 v3, v99, 0x3e38aa3b, v2
	v_exp_f32_e32 v99, v3
	v_fmamk_f32 v3, v100, 0x3e38aa3b, v2
	v_exp_f32_e32 v100, v3
	v_fmamk_f32 v3, v101, 0x3e38aa3b, v2
	v_exp_f32_e32 v101, v3
	v_fmamk_f32 v3, v102, 0x3e38aa3b, v2
	v_exp_f32_e32 v102, v3
	v_fmamk_f32 v3, v103, 0x3e38aa3b, v2
	v_exp_f32_e32 v103, v3
	v_fmamk_f32 v3, v104, 0x3e38aa3b, v2
	v_exp_f32_e32 v104, v3
	v_fmamk_f32 v3, v105, 0x3e38aa3b, v2
	v_exp_f32_e32 v105, v3
	v_fmamk_f32 v3, v106, 0x3e38aa3b, v2
	v_exp_f32_e32 v106, v3
	v_fmamk_f32 v3, v107, 0x3e38aa3b, v2
	v_exp_f32_e32 v107, v3
	v_fmamk_f32 v3, v108, 0x3e38aa3b, v2
	v_exp_f32_e32 v108, v3
	v_fmamk_f32 v3, v109, 0x3e38aa3b, v2
	v_exp_f32_e32 v109, v3
	v_fmamk_f32 v3, v110, 0x3e38aa3b, v2
	v_exp_f32_e32 v110, v3
	v_fmamk_f32 v3, v111, 0x3e38aa3b, v2
	v_exp_f32_e32 v111, v3
	v_sub_f32_e32 v0, v193, v0
	v_mul_f32_e32 v0, 0x3e38aa3b, v0
	v_exp_f32_e32 v0, v0
	v_add_f32_e32 v2, 0, v80
	v_cndmask_b32_e64 v194, v0, 1.0, s[0:1]
	v_mov_b32_e32 v193, v14
	v_add_f32_e32 v2, v81, v2
	v_add_f32_e32 v2, v82, v2
	v_add_f32_e32 v2, v83, v2
	v_add_f32_e32 v2, v84, v2
	v_add_f32_e32 v2, v85, v2
	v_add_f32_e32 v2, v86, v2
	v_add_f32_e32 v2, v87, v2
	v_add_f32_e32 v2, v88, v2
	v_add_f32_e32 v2, v89, v2
	v_add_f32_e32 v2, v90, v2
	v_add_f32_e32 v2, v91, v2
	v_add_f32_e32 v2, v92, v2
	v_add_f32_e32 v2, v93, v2
	v_add_f32_e32 v2, v94, v2
	v_add_f32_e32 v2, v95, v2
	v_add_f32_e32 v2, v96, v2
	v_add_f32_e32 v2, v97, v2
	v_add_f32_e32 v2, v98, v2
	v_add_f32_e32 v2, v99, v2
	v_add_f32_e32 v2, v100, v2
	v_add_f32_e32 v2, v101, v2
	v_add_f32_e32 v2, v102, v2
	v_add_f32_e32 v2, v103, v2
	v_add_f32_e32 v2, v104, v2
	v_add_f32_e32 v2, v105, v2
	v_add_f32_e32 v2, v106, v2
	v_add_f32_e32 v2, v107, v2
	v_add_f32_e32 v2, v108, v2
	v_add_f32_e32 v2, v109, v2
	v_add_f32_e32 v2, v110, v2
	v_add_f32_e32 v15, v111, v2
	v_mov_b32_e32 v195, v15
	v_cvt_pk_bf16_f32 v80, v80, v81
	v_cvt_pk_bf16_f32 v81, v82, v83
	v_cvt_pk_bf16_f32 v82, v84, v85
	v_cvt_pk_bf16_f32 v83, v86, v87
	v_cvt_pk_bf16_f32 v84, v88, v89
	v_cvt_pk_bf16_f32 v85, v90, v91
	v_cvt_pk_bf16_f32 v86, v92, v93
	v_cvt_pk_bf16_f32 v87, v94, v95
	v_cvt_pk_bf16_f32 v88, v96, v97
	v_cvt_pk_bf16_f32 v89, v98, v99
	v_cvt_pk_bf16_f32 v90, v100, v101
	v_cvt_pk_bf16_f32 v91, v102, v103
	v_cvt_pk_bf16_f32 v92, v104, v105
	v_cvt_pk_bf16_f32 v93, v106, v107
	v_cvt_pk_bf16_f32 v94, v108, v109
	v_cvt_pk_bf16_f32 v95, v110, v111
	s_nop 1
	v_permlane32_swap_b32_e32 v15, v195
	v_permlane32_swap_b32_e32 v80, v82
	v_permlane32_swap_b32_e32 v81, v83
	v_permlane32_swap_b32_e32 v84, v86
	v_permlane32_swap_b32_e32 v85, v87
	v_permlane32_swap_b32_e32 v88, v90
	v_permlane32_swap_b32_e32 v89, v91
	v_permlane32_swap_b32_e32 v92, v94
	v_permlane32_swap_b32_e32 v93, v95
	v_add_f32_e32 v15, v15, v195
	v_fmac_f32_e32 v15, v192, v194
	v_mov_b32_e32 v192, v15
	v_mov_b32_e32 v194, 1.0
	s_branch .Lnl_qe
.Lnl_me:
	v_cmp_gt_f32_e32 vcc, 1.0, v194
	s_cbranch_vccz .Lnl_nors_e
	v_pk_mul_f32 v[78:79], v[78:79], v[194:195] op_sel_hi:[1,0]
	v_pk_mul_f32 v[76:77], v[76:77], v[194:195] op_sel_hi:[1,0]
	v_pk_mul_f32 v[74:75], v[74:75], v[194:195] op_sel_hi:[1,0]
	v_pk_mul_f32 v[72:73], v[72:73], v[194:195] op_sel_hi:[1,0]
	v_pk_mul_f32 v[70:71], v[70:71], v[194:195] op_sel_hi:[1,0]
	v_pk_mul_f32 v[68:69], v[68:69], v[194:195] op_sel_hi:[1,0]
	v_pk_mul_f32 v[66:67], v[66:67], v[194:195] op_sel_hi:[1,0]
	v_pk_mul_f32 v[64:65], v[64:65], v[194:195] op_sel_hi:[1,0]
	v_pk_mul_f32 v[62:63], v[62:63], v[194:195] op_sel_hi:[1,0]
	v_pk_mul_f32 v[60:61], v[60:61], v[194:195] op_sel_hi:[1,0]
	v_pk_mul_f32 v[58:59], v[58:59], v[194:195] op_sel_hi:[1,0]
	v_pk_mul_f32 v[56:57], v[56:57], v[194:195] op_sel_hi:[1,0]
	v_pk_mul_f32 v[54:55], v[54:55], v[194:195] op_sel_hi:[1,0]
	v_pk_mul_f32 v[52:53], v[52:53], v[194:195] op_sel_hi:[1,0]
	v_pk_mul_f32 v[50:51], v[50:51], v[194:195] op_sel_hi:[1,0]
	v_pk_mul_f32 v[48:49], v[48:49], v[194:195] op_sel_hi:[1,0]
	v_pk_mul_f32 v[46:47], v[46:47], v[194:195] op_sel_hi:[1,0]
	v_pk_mul_f32 v[44:45], v[44:45], v[194:195] op_sel_hi:[1,0]
	v_pk_mul_f32 v[42:43], v[42:43], v[194:195] op_sel_hi:[1,0]
	v_pk_mul_f32 v[40:41], v[40:41], v[194:195] op_sel_hi:[1,0]
	v_pk_mul_f32 v[38:39], v[38:39], v[194:195] op_sel_hi:[1,0]
	v_pk_mul_f32 v[36:37], v[36:37], v[194:195] op_sel_hi:[1,0]
	v_pk_mul_f32 v[34:35], v[34:35], v[194:195] op_sel_hi:[1,0]
	v_pk_mul_f32 v[32:33], v[32:33], v[194:195] op_sel_hi:[1,0]
	v_pk_mul_f32 v[30:31], v[30:31], v[194:195] op_sel_hi:[1,0]
	v_pk_mul_f32 v[28:29], v[28:29], v[194:195] op_sel_hi:[1,0]
	v_pk_mul_f32 v[26:27], v[26:27], v[194:195] op_sel_hi:[1,0]
	v_pk_mul_f32 v[24:25], v[24:25], v[194:195] op_sel_hi:[1,0]
	v_pk_mul_f32 v[22:23], v[22:23], v[194:195] op_sel_hi:[1,0]
	v_pk_mul_f32 v[20:21], v[20:21], v[194:195] op_sel_hi:[1,0]
	v_pk_mul_f32 v[18:19], v[18:19], v[194:195] op_sel_hi:[1,0]
	v_pk_mul_f32 v[16:17], v[16:17], v[194:195] op_sel_hi:[1,0]
.Lnl_nors_e:
	s_add_i32 s0, s10, 0x18000
	s_and_b32 s0, s0, 0x18000
	v_add_u32_e32 v13, s0, v191
	ds_read_b64_tr_b16 v[128:129], v13 offset:0
	ds_read_b64_tr_b16 v[130:131], v13 offset:2048
	ds_read_b64_tr_b16 v[132:133], v13 offset:512
	ds_read_b64_tr_b16 v[134:135], v13 offset:2560
	ds_read_b64_tr_b16 v[136:137], v13 offset:1024
	ds_read_b64_tr_b16 v[138:139], v13 offset:3072
	ds_read_b64_tr_b16 v[140:141], v13 offset:1536
	ds_read_b64_tr_b16 v[142:143], v13 offset:3584
	v_max_f32_e32 v0, v81, v81
	v_max_f32_e32 v2, v80, v80
	v_max_f32_e32 v0, v2, v0
	v_max3_f32 v0, v0, v82, v83
	v_max3_f32 v0, v0, v84, v85
	v_max3_f32 v0, v0, v86, v87
	v_max3_f32 v0, v0, v88, v89
	v_max3_f32 v0, v0, v90, v91
	v_max3_f32 v0, v0, v92, v93
	v_max3_f32 v0, v0, v94, v95
	v_max3_f32 v0, v0, v96, v97
	v_max3_f32 v0, v0, v98, v99
	v_max3_f32 v0, v0, v100, v101
	v_max3_f32 v0, v0, v102, v103
	v_max3_f32 v0, v0, v104, v105
	v_max3_f32 v0, v0, v106, v107
	v_max3_f32 v0, v0, v108, v109
	v_max3_f32 v0, v0, v110, v111
	v_mov_b32_e32 v2, v0
	s_nop 1
	v_permlane32_swap_b32_e32 v0, v2
	v_max_f32_e32 v2, v2, v2
	v_max_f32_e32 v0, v0, v0
	v_max_f32_e32 v0, v0, v2
	v_sub_f32_e32 v2, v0, v193
	v_cmp_ge_f32_e64 s[0:1], s27, v2
	v_max_f32_e32 v0, v0, v0
	v_max_f32_e32 v2, v193, v193
	v_max_f32_e32 v0, v2, v0
	s_cmp_eq_u64 s[0:1], exec
	s_waitcnt lgkmcnt(0)
	s_cselect_b64 s[0:1], -1, 0
	v_cndmask_b32_e64 v14, v0, v193, s[0:1]
	v_mul_f32_e32 v2, 0xbe38aa3b, v14
	v_fmamk_f32 v3, v80, 0x3e38aa3b, v2
	v_exp_f32_e32 v80, v3
	v_mfma_f32_32x32x16_bf16 v[64:79], v[128:131], v[112:115], v[64:79]
	v_fmamk_f32 v3, v81, 0x3e38aa3b, v2
	v_exp_f32_e32 v81, v3
	v_fmamk_f32 v3, v82, 0x3e38aa3b, v2
	v_exp_f32_e32 v82, v3
	v_fmamk_f32 v3, v83, 0x3e38aa3b, v2
	v_exp_f32_e32 v83, v3
	ds_read_b64_tr_b16 v[160:161], v13 offset:4096
	ds_read_b64_tr_b16 v[162:163], v13 offset:6144
	ds_read_b64_tr_b16 v[182:183], v13 offset:4608
	ds_read_b64_tr_b16 v[184:185], v13 offset:6656
	ds_read_b64_tr_b16 v[198:199], v13 offset:5120
	ds_read_b64_tr_b16 v[200:201], v13 offset:7168
	ds_read_b64_tr_b16 v[202:203], v13 offset:5632
	ds_read_b64_tr_b16 v[204:205], v13 offset:7680
	v_fmamk_f32 v3, v84, 0x3e38aa3b, v2
	v_exp_f32_e32 v84, v3
	v_fmamk_f32 v3, v85, 0x3e38aa3b, v2
	v_exp_f32_e32 v85, v3
	v_fmamk_f32 v3, v86, 0x3e38aa3b, v2
	v_mfma_f32_32x32x16_bf16 v[48:63], v[132:135], v[112:115], v[48:63]
	v_exp_f32_e32 v86, v3
	v_fmamk_f32 v3, v87, 0x3e38aa3b, v2
	v_exp_f32_e32 v87, v3
	v_fmamk_f32 v3, v88, 0x3e38aa3b, v2
	v_exp_f32_e32 v88, v3
	v_fmamk_f32 v3, v89, 0x3e38aa3b, v2
	v_mfma_f32_32x32x16_bf16 v[32:47], v[136:139], v[112:115], v[32:47]
	v_exp_f32_e32 v89, v3
	v_fmamk_f32 v3, v90, 0x3e38aa3b, v2
	v_exp_f32_e32 v90, v3
	v_fmamk_f32 v3, v91, 0x3e38aa3b, v2
	v_exp_f32_e32 v91, v3
	v_mfma_f32_32x32x16_bf16 v[16:31], v[140:143], v[112:115], v[16:31]
	v_fmamk_f32 v3, v92, 0x3e38aa3b, v2
	v_exp_f32_e32 v92, v3
	v_fmamk_f32 v3, v93, 0x3e38aa3b, v2
	v_exp_f32_e32 v93, v3
	v_fmamk_f32 v3, v94, 0x3e38aa3b, v2
	v_exp_f32_e32 v94, v3
	s_waitcnt lgkmcnt(0)
	v_fmamk_f32 v3, v95, 0x3e38aa3b, v2
	v_exp_f32_e32 v95, v3
	v_fmamk_f32 v3, v96, 0x3e38aa3b, v2
	v_exp_f32_e32 v96, v3
	v_fmamk_f32 v3, v97, 0x3e38aa3b, v2
	v_mfma_f32_32x32x16_bf16 v[64:79], v[160:163], v[116:119], v[64:79]
	v_exp_f32_e32 v97, v3
	v_fmamk_f32 v3, v98, 0x3e38aa3b, v2
	v_exp_f32_e32 v98, v3
	v_fmamk_f32 v3, v99, 0x3e38aa3b, v2
	v_exp_f32_e32 v99, v3
	v_fmamk_f32 v3, v100, 0x3e38aa3b, v2
	ds_read_b64_tr_b16 v[128:129], v13 offset:8192
	ds_read_b64_tr_b16 v[130:131], v13 offset:10240
	ds_read_b64_tr_b16 v[132:133], v13 offset:8704
	ds_read_b64_tr_b16 v[134:135], v13 offset:10752
	ds_read_b64_tr_b16 v[136:137], v13 offset:9216
	ds_read_b64_tr_b16 v[138:139], v13 offset:11264
	ds_read_b64_tr_b16 v[140:141], v13 offset:9728
	ds_read_b64_tr_b16 v[142:143], v13 offset:11776
	v_exp_f32_e32 v100, v3
	v_fmamk_f32 v3, v101, 0x3e38aa3b, v2
	v_exp_f32_e32 v101, v3
	v_fmamk_f32 v3, v102, 0x3e38aa3b, v2
	v_exp_f32_e32 v102, v3
	v_fmamk_f32 v3, v103, 0x3e38aa3b, v2
	v_mfma_f32_32x32x16_bf16 v[48:63], v[182:185], v[116:119], v[48:63]
	v_exp_f32_e32 v103, v3
	v_fmamk_f32 v3, v104, 0x3e38aa3b, v2
	v_exp_f32_e32 v104, v3
	v_fmamk_f32 v3, v105, 0x3e38aa3b, v2
	v_exp_f32_e32 v105, v3
	v_mfma_f32_32x32x16_bf16 v[32:47], v[198:201], v[116:119], v[32:47]
	v_fmamk_f32 v3, v106, 0x3e38aa3b, v2
	v_exp_f32_e32 v106, v3
	v_fmamk_f32 v3, v107, 0x3e38aa3b, v2
	v_exp_f32_e32 v107, v3
	v_fmamk_f32 v3, v108, 0x3e38aa3b, v2
	v_exp_f32_e32 v108, v3
	v_mfma_f32_32x32x16_bf16 v[16:31], v[202:205], v[116:119], v[16:31]
	v_fmamk_f32 v3, v109, 0x3e38aa3b, v2
	v_exp_f32_e32 v109, v3
	v_fmamk_f32 v3, v110, 0x3e38aa3b, v2
	v_exp_f32_e32 v110, v3
	v_fmamk_f32 v3, v111, 0x3e38aa3b, v2
	s_waitcnt lgkmcnt(0)
	v_exp_f32_e32 v111, v3
	v_sub_f32_e32 v0, v193, v0
	v_mul_f32_e32 v0, 0x3e38aa3b, v0
	v_exp_f32_e32 v0, v0
	v_add_f32_e32 v2, 0, v80
	v_cndmask_b32_e64 v194, v0, 1.0, s[0:1]
	v_mfma_f32_32x32x16_bf16 v[64:79], v[128:131], v[120:123], v[64:79]
	v_mov_b32_e32 v193, v14
	v_add_f32_e32 v2, v81, v2
	v_add_f32_e32 v2, v82, v2
	v_add_f32_e32 v2, v83, v2
	v_add_f32_e32 v2, v84, v2
	ds_read_b64_tr_b16 v[160:161], v13 offset:12288
	ds_read_b64_tr_b16 v[162:163], v13 offset:14336
	ds_read_b64_tr_b16 v[182:183], v13 offset:12800
	ds_read_b64_tr_b16 v[184:185], v13 offset:14848
	ds_read_b64_tr_b16 v[198:199], v13 offset:13312
	ds_read_b64_tr_b16 v[200:201], v13 offset:15360
	ds_read_b64_tr_b16 v[202:203], v13 offset:13824
	ds_read_b64_tr_b16 v[204:205], v13 offset:15872
	v_add_f32_e32 v2, v85, v2
	v_add_f32_e32 v2, v86, v2
	v_add_f32_e32 v2, v87, v2
	v_add_f32_e32 v2, v88, v2
	v_add_f32_e32 v2, v89, v2
	v_add_f32_e32 v2, v90, v2
	v_mfma_f32_32x32x16_bf16 v[48:63], v[132:135], v[120:123], v[48:63]
	v_add_f32_e32 v2, v91, v2
	v_add_f32_e32 v2, v92, v2
	v_add_f32_e32 v2, v93, v2
	v_add_f32_e32 v2, v94, v2
	v_add_f32_e32 v2, v95, v2
	v_add_f32_e32 v2, v96, v2
	v_mfma_f32_32x32x16_bf16 v[32:47], v[136:139], v[120:123], v[32:47]
	v_add_f32_e32 v2, v97, v2
	v_add_f32_e32 v2, v98, v2
	v_add_f32_e32 v2, v99, v2
	v_add_f32_e32 v2, v100, v2
	v_add_f32_e32 v2, v101, v2
	v_mfma_f32_32x32x16_bf16 v[16:31], v[140:143], v[120:123], v[16:31]
	v_add_f32_e32 v2, v102, v2
	v_add_f32_e32 v2, v103, v2
	v_add_f32_e32 v2, v104, v2
	v_add_f32_e32 v2, v105, v2
	v_add_f32_e32 v2, v106, v2
	v_add_f32_e32 v2, v107, v2
	s_waitcnt lgkmcnt(0)
	v_add_f32_e32 v2, v108, v2
	v_add_f32_e32 v2, v109, v2
	v_add_f32_e32 v2, v110, v2
	v_add_f32_e32 v15, v111, v2
	v_mov_b32_e32 v195, v15
	v_mfma_f32_32x32x16_bf16 v[64:79], v[160:163], v[124:127], v[64:79]
	v_cvt_pk_bf16_f32 v80, v80, v81
	v_cvt_pk_bf16_f32 v81, v82, v83
	v_cvt_pk_bf16_f32 v82, v84, v85
	v_cvt_pk_bf16_f32 v83, v86, v87
	v_cvt_pk_bf16_f32 v84, v88, v89
	v_cvt_pk_bf16_f32 v85, v90, v91
	v_mfma_f32_32x32x16_bf16 v[48:63], v[182:185], v[124:127], v[48:63]
	v_cvt_pk_bf16_f32 v86, v92, v93
	v_cvt_pk_bf16_f32 v87, v94, v95
	v_cvt_pk_bf16_f32 v88, v96, v97
	v_cvt_pk_bf16_f32 v89, v98, v99
	v_cvt_pk_bf16_f32 v90, v100, v101
	v_mfma_f32_32x32x16_bf16 v[32:47], v[198:201], v[124:127], v[32:47]
	v_cvt_pk_bf16_f32 v91, v102, v103
	v_cvt_pk_bf16_f32 v92, v104, v105
	v_cvt_pk_bf16_f32 v93, v106, v107
	v_cvt_pk_bf16_f32 v94, v108, v109
	v_cvt_pk_bf16_f32 v95, v110, v111
	s_nop 1
	v_mfma_f32_32x32x16_bf16 v[16:31], v[202:205], v[124:127], v[16:31]
	v_permlane32_swap_b32_e32 v15, v195
	v_permlane32_swap_b32_e32 v80, v82
	v_permlane32_swap_b32_e32 v81, v83
	v_permlane32_swap_b32_e32 v84, v86
	v_permlane32_swap_b32_e32 v85, v87
	v_permlane32_swap_b32_e32 v88, v90
	v_permlane32_swap_b32_e32 v89, v91
	v_permlane32_swap_b32_e32 v92, v94
	v_permlane32_swap_b32_e32 v93, v95
	v_add_f32_e32 v15, v15, v195
	v_fmac_f32_e32 v15, v192, v194
	v_mov_b32_e32 v192, v15
.Lnl_qe:
	s_add_i32 s96, s11, 1
	s_cmp_lt_i32 s96, s8
	s_cbranch_scc0 .Lnl_noqe
		s_add_i32 s0, s10, 0x8000
		s_and_b32 s0, s0, 0x18000
		s_add_i32 s0, s0, 0
		v_add_u32_e32 v0, s0, v175
		ds_read_b128 v[2:5], v0 offset:0
		ds_read_b128 v[6:9], v0 offset:0x2000
		v_add_u32_e32 v0, s0, v176
		ds_read_b128 v[10:13], v0 offset:0
		ds_read_b128 v[160:163], v0 offset:0x2000
		s_waitcnt lgkmcnt(0)
		v_mfma_f32_32x32x16_bf16 v[112:127], v[2:5], v[144:147], 0
		v_add_u32_e32 v0, s0, v177
		ds_read_b128 v[2:5], v0 offset:0
		v_mfma_f32_32x32x16_bf16 v[128:143], v[6:9], v[144:147], 0
		ds_read_b128 v[6:9], v0 offset:0x2000
		v_add_u32_e32 v0, s0, v189
		v_mfma_f32_32x32x16_bf16 v[112:127], v[10:13], v[148:151], v[112:127]
		ds_read_b128 v[10:13], v0 offset:0
		ds_read_b128 v[182:185], v0 offset:0x2000
		s_waitcnt lgkmcnt(0)
		v_mfma_f32_32x32x16_bf16 v[128:143], v[160:163], v[148:151], v[128:143]
		v_mfma_f32_32x32x16_bf16 v[112:127], v[2:5], v[152:155], v[112:127]
		v_mfma_f32_32x32x16_bf16 v[128:143], v[6:9], v[152:155], v[128:143]
		v_mfma_f32_32x32x16_bf16 v[112:127], v[10:13], v[156:159], v[112:127]
		v_mfma_f32_32x32x16_bf16 v[128:143], v[182:185], v[156:159], v[128:143]
	s_nop 7
	s_nop 3
.Lnl_noqe:
	s_add_i32 s96, s11, 3
	s_cmp_lt_i32 s96, s9
	s_cbranch_scc1 .Lnl_wo
	s_waitcnt vmcnt(0)
	s_branch .Lnl_bo
.Lnl_wo:
	s_cmp_eq_u32 s11, 0
	s_cbranch_scc1 .Lnl_wo2
	s_waitcnt vmcnt(4)
	s_branch .Lnl_bo
.Lnl_wo2:
	s_waitcnt vmcnt(2)
.Lnl_bo:
	s_barrier
	s_cmp_lt_i32 s96, s9
	s_cbranch_scc0 .Lnl_noVo
	s_add_i32 s12, s10, 0x18000
	s_and_b32 s12, s12, 0x18000
	s_add_i32 s12, s90, s12
	v_lshl_add_u64 v[2:3], s[78:79], 0, v[172:173]
	v_lshl_add_u64 v[2:3], v[2:3], 0, s[50:51]
	s_mov_b32 m0, s12
	s_nop 0
	global_load_lds_dwordx4 v[2:3], off
	v_lshl_add_u64 v[2:3], s[78:79], 0, v[170:171]
	v_lshl_add_u64 v[2:3], v[2:3], 0, s[50:51]
	s_add_i32 m0, s12, 0x2000
	s_nop 0
	global_load_lds_dwordx4 v[2:3], off
.Lnl_noVo:
	s_add_i32 s97, s11, 4
	s_cmp_lt_i32 s97, s9
	s_cbranch_scc0 .Lnl_noKo
	s_add_i32 s12, s10, 0x0
	s_and_b32 s12, s12, 0x18000
	s_add_i32 s12, s90, s12
	v_lshl_add_u64 v[2:3], s[78:79], 0, v[168:169]
	v_lshl_add_u64 v[2:3], v[2:3], 0, s[56:57]
	s_add_i32 m0, s12, 0x4000
	s_nop 0
	global_load_lds_dwordx4 v[2:3], off
	v_lshl_add_u64 v[2:3], s[78:79], 0, v[166:167]
	v_lshl_add_u64 v[2:3], v[2:3], 0, s[56:57]
	s_add_i32 m0, s12, 0x6000
	s_nop 0
	global_load_lds_dwordx4 v[2:3], off
.Lnl_noKo:
	s_add_i32 s96, s11, 1
	s_cmp_lt_i32 s96, s8
	s_cbranch_scc1 .Lnl_mo
	v_cmp_gt_f32_e32 vcc, 1.0, v194
	s_cbranch_vccz .Lnl_nors_po
	v_pk_mul_f32 v[78:79], v[78:79], v[194:195] op_sel_hi:[1,0]
	v_pk_mul_f32 v[76:77], v[76:77], v[194:195] op_sel_hi:[1,0]
	v_pk_mul_f32 v[74:75], v[74:75], v[194:195] op_sel_hi:[1,0]
	v_pk_mul_f32 v[72:73], v[72:73], v[194:195] op_sel_hi:[1,0]
	v_pk_mul_f32 v[70:71], v[70:71], v[194:195] op_sel_hi:[1,0]
	v_pk_mul_f32 v[68:69], v[68:69], v[194:195] op_sel_hi:[1,0]
	v_pk_mul_f32 v[66:67], v[66:67], v[194:195] op_sel_hi:[1,0]
	v_pk_mul_f32 v[64:65], v[64:65], v[194:195] op_sel_hi:[1,0]
	v_pk_mul_f32 v[62:63], v[62:63], v[194:195] op_sel_hi:[1,0]
	v_pk_mul_f32 v[60:61], v[60:61], v[194:195] op_sel_hi:[1,0]
	v_pk_mul_f32 v[58:59], v[58:59], v[194:195] op_sel_hi:[1,0]
	v_pk_mul_f32 v[56:57], v[56:57], v[194:195] op_sel_hi:[1,0]
	v_pk_mul_f32 v[54:55], v[54:55], v[194:195] op_sel_hi:[1,0]
	v_pk_mul_f32 v[52:53], v[52:53], v[194:195] op_sel_hi:[1,0]
	v_pk_mul_f32 v[50:51], v[50:51], v[194:195] op_sel_hi:[1,0]
	v_pk_mul_f32 v[48:49], v[48:49], v[194:195] op_sel_hi:[1,0]
	v_pk_mul_f32 v[46:47], v[46:47], v[194:195] op_sel_hi:[1,0]
	v_pk_mul_f32 v[44:45], v[44:45], v[194:195] op_sel_hi:[1,0]
	v_pk_mul_f32 v[42:43], v[42:43], v[194:195] op_sel_hi:[1,0]
	v_pk_mul_f32 v[40:41], v[40:41], v[194:195] op_sel_hi:[1,0]
	v_pk_mul_f32 v[38:39], v[38:39], v[194:195] op_sel_hi:[1,0]
	v_pk_mul_f32 v[36:37], v[36:37], v[194:195] op_sel_hi:[1,0]
	v_pk_mul_f32 v[34:35], v[34:35], v[194:195] op_sel_hi:[1,0]
	v_pk_mul_f32 v[32:33], v[32:33], v[194:195] op_sel_hi:[1,0]
	v_pk_mul_f32 v[30:31], v[30:31], v[194:195] op_sel_hi:[1,0]
	v_pk_mul_f32 v[28:29], v[28:29], v[194:195] op_sel_hi:[1,0]
	v_pk_mul_f32 v[26:27], v[26:27], v[194:195] op_sel_hi:[1,0]
	v_pk_mul_f32 v[24:25], v[24:25], v[194:195] op_sel_hi:[1,0]
	v_pk_mul_f32 v[22:23], v[22:23], v[194:195] op_sel_hi:[1,0]
	v_pk_mul_f32 v[20:21], v[20:21], v[194:195] op_sel_hi:[1,0]
	v_pk_mul_f32 v[18:19], v[18:19], v[194:195] op_sel_hi:[1,0]
	v_pk_mul_f32 v[16:17], v[16:17], v[194:195] op_sel_hi:[1,0]
.Lnl_nors_po:
	s_add_i32 s0, s10, 0x0
	s_and_b32 s0, s0, 0x18000
	v_add_u32_e32 v13, s0, v191
	ds_read_b64_tr_b16 v[128:129], v13 offset:0
	ds_read_b64_tr_b16 v[130:131], v13 offset:2048
	ds_read_b64_tr_b16 v[132:133], v13 offset:512
	ds_read_b64_tr_b16 v[134:135], v13 offset:2560
	ds_read_b64_tr_b16 v[136:137], v13 offset:1024
	ds_read_b64_tr_b16 v[138:139], v13 offset:3072
	ds_read_b64_tr_b16 v[140:141], v13 offset:1536
	ds_read_b64_tr_b16 v[142:143], v13 offset:3584
	s_waitcnt lgkmcnt(0)
	v_mfma_f32_32x32x16_bf16 v[64:79], v[128:131], v[80:83], v[64:79]
	ds_read_b64_tr_b16 v[160:161], v13 offset:4096
	ds_read_b64_tr_b16 v[162:163], v13 offset:6144
	ds_read_b64_tr_b16 v[182:183], v13 offset:4608
	ds_read_b64_tr_b16 v[184:185], v13 offset:6656
	ds_read_b64_tr_b16 v[198:199], v13 offset:5120
	ds_read_b64_tr_b16 v[200:201], v13 offset:7168
	ds_read_b64_tr_b16 v[202:203], v13 offset:5632
	ds_read_b64_tr_b16 v[204:205], v13 offset:7680
	v_mfma_f32_32x32x16_bf16 v[48:63], v[132:135], v[80:83], v[48:63]
	v_mfma_f32_32x32x16_bf16 v[32:47], v[136:139], v[80:83], v[32:47]
	v_mfma_f32_32x32x16_bf16 v[16:31], v[140:143], v[80:83], v[16:31]
	s_waitcnt lgkmcnt(0)
	v_mfma_f32_32x32x16_bf16 v[64:79], v[160:163], v[84:87], v[64:79]
	ds_read_b64_tr_b16 v[128:129], v13 offset:8192
	ds_read_b64_tr_b16 v[130:131], v13 offset:10240
	ds_read_b64_tr_b16 v[132:133], v13 offset:8704
	ds_read_b64_tr_b16 v[134:135], v13 offset:10752
	ds_read_b64_tr_b16 v[136:137], v13 offset:9216
	ds_read_b64_tr_b16 v[138:139], v13 offset:11264
	ds_read_b64_tr_b16 v[140:141], v13 offset:9728
	ds_read_b64_tr_b16 v[142:143], v13 offset:11776
	v_mfma_f32_32x32x16_bf16 v[48:63], v[182:185], v[84:87], v[48:63]
	v_mfma_f32_32x32x16_bf16 v[32:47], v[198:201], v[84:87], v[32:47]
	v_mfma_f32_32x32x16_bf16 v[16:31], v[202:205], v[84:87], v[16:31]
	s_waitcnt lgkmcnt(0)
	v_mfma_f32_32x32x16_bf16 v[64:79], v[128:131], v[88:91], v[64:79]
	ds_read_b64_tr_b16 v[160:161], v13 offset:12288
	ds_read_b64_tr_b16 v[162:163], v13 offset:14336
	ds_read_b64_tr_b16 v[182:183], v13 offset:12800
	ds_read_b64_tr_b16 v[184:185], v13 offset:14848
	ds_read_b64_tr_b16 v[198:199], v13 offset:13312
	ds_read_b64_tr_b16 v[200:201], v13 offset:15360
	ds_read_b64_tr_b16 v[202:203], v13 offset:13824
	ds_read_b64_tr_b16 v[204:205], v13 offset:15872
	v_mfma_f32_32x32x16_bf16 v[48:63], v[132:135], v[88:91], v[48:63]
	v_mfma_f32_32x32x16_bf16 v[32:47], v[136:139], v[88:91], v[32:47]
	v_mfma_f32_32x32x16_bf16 v[16:31], v[140:143], v[88:91], v[16:31]
	s_waitcnt lgkmcnt(0)
	v_mfma_f32_32x32x16_bf16 v[64:79], v[160:163], v[92:95], v[64:79]
	v_mfma_f32_32x32x16_bf16 v[48:63], v[182:185], v[92:95], v[48:63]
	v_mfma_f32_32x32x16_bf16 v[32:47], v[198:201], v[92:95], v[32:47]
	v_mfma_f32_32x32x16_bf16 v[16:31], v[202:205], v[92:95], v[16:31]
	s_branch .Lnl_qo

.Lnl_nors_o:
	s_add_i32 s0, s10, 0x0
	s_and_b32 s0, s0, 0x18000
	v_add_u32_e32 v13, s0, v191
	ds_read_b64_tr_b16 v[96:97], v13 offset:0
	ds_read_b64_tr_b16 v[98:99], v13 offset:2048
	ds_read_b64_tr_b16 v[100:101], v13 offset:512
	ds_read_b64_tr_b16 v[102:103], v13 offset:2560
	ds_read_b64_tr_b16 v[104:105], v13 offset:1024
	ds_read_b64_tr_b16 v[106:107], v13 offset:3072
	ds_read_b64_tr_b16 v[108:109], v13 offset:1536
	ds_read_b64_tr_b16 v[110:111], v13 offset:3584
	v_max_f32_e32 v0, v113, v113
	v_max_f32_e32 v2, v112, v112
	v_max_f32_e32 v0, v2, v0
	v_max3_f32 v0, v0, v114, v115
	v_max3_f32 v0, v0, v116, v117
	v_max3_f32 v0, v0, v118, v119
	v_max3_f32 v0, v0, v120, v121
	v_max3_f32 v0, v0, v122, v123
	v_max3_f32 v0, v0, v124, v125
	v_max3_f32 v0, v0, v126, v127
	v_max3_f32 v0, v0, v128, v129
	v_max3_f32 v0, v0, v130, v131
	v_max3_f32 v0, v0, v132, v133
	v_max3_f32 v0, v0, v134, v135
	v_max3_f32 v0, v0, v136, v137
	v_max3_f32 v0, v0, v138, v139
	v_max3_f32 v0, v0, v140, v141
	v_max3_f32 v0, v0, v142, v143
	v_mov_b32_e32 v2, v0
	s_nop 1
	v_permlane32_swap_b32_e32 v0, v2
	v_max_f32_e32 v2, v2, v2
	v_max_f32_e32 v0, v0, v0
	v_max_f32_e32 v0, v0, v2
	v_sub_f32_e32 v2, v0, v193
	v_cmp_ge_f32_e64 s[0:1], s27, v2
	v_max_f32_e32 v0, v0, v0
	v_max_f32_e32 v2, v193, v193
	v_max_f32_e32 v0, v2, v0
	s_cmp_eq_u64 s[0:1], exec
	s_waitcnt lgkmcnt(0)
	s_cselect_b64 s[0:1], -1, 0
	v_cndmask_b32_e64 v14, v0, v193, s[0:1]
	v_mul_f32_e32 v2, 0xbe38aa3b, v14
	v_fmamk_f32 v3, v112, 0x3e38aa3b, v2
	v_exp_f32_e32 v112, v3
	v_mfma_f32_32x32x16_bf16 v[64:79], v[96:99], v[80:83], v[64:79]
	v_fmamk_f32 v3, v113, 0x3e38aa3b, v2
	v_exp_f32_e32 v113, v3
	v_fmamk_f32 v3, v114, 0x3e38aa3b, v2
	v_exp_f32_e32 v114, v3
	v_fmamk_f32 v3, v115, 0x3e38aa3b, v2
	v_exp_f32_e32 v115, v3
	ds_read_b64_tr_b16 v[160:161], v13 offset:4096
	ds_read_b64_tr_b16 v[162:163], v13 offset:6144
	ds_read_b64_tr_b16 v[182:183], v13 offset:4608
	ds_read_b64_tr_b16 v[184:185], v13 offset:6656
	ds_read_b64_tr_b16 v[198:199], v13 offset:5120
	ds_read_b64_tr_b16 v[200:201], v13 offset:7168
	ds_read_b64_tr_b16 v[202:203], v13 offset:5632
	ds_read_b64_tr_b16 v[204:205], v13 offset:7680
	v_fmamk_f32 v3, v116, 0x3e38aa3b, v2
	v_exp_f32_e32 v116, v3
	v_fmamk_f32 v3, v117, 0x3e38aa3b, v2
	v_exp_f32_e32 v117, v3
	v_fmamk_f32 v3, v118, 0x3e38aa3b, v2
	v_mfma_f32_32x32x16_bf16 v[48:63], v[100:103], v[80:83], v[48:63]
	v_exp_f32_e32 v118, v3
	v_fmamk_f32 v3, v119, 0x3e38aa3b, v2
	v_exp_f32_e32 v119, v3
	v_fmamk_f32 v3, v120, 0x3e38aa3b, v2
	v_exp_f32_e32 v120, v3
	v_fmamk_f32 v3, v121, 0x3e38aa3b, v2
	v_mfma_f32_32x32x16_bf16 v[32:47], v[104:107], v[80:83], v[32:47]
	v_exp_f32_e32 v121, v3
	v_fmamk_f32 v3, v122, 0x3e38aa3b, v2
	v_exp_f32_e32 v122, v3
	v_fmamk_f32 v3, v123, 0x3e38aa3b, v2
	v_exp_f32_e32 v123, v3
	v_mfma_f32_32x32x16_bf16 v[16:31], v[108:111], v[80:83], v[16:31]
	v_fmamk_f32 v3, v124, 0x3e38aa3b, v2
	v_exp_f32_e32 v124, v3
	v_fmamk_f32 v3, v125, 0x3e38aa3b, v2
	v_exp_f32_e32 v125, v3
	v_fmamk_f32 v3, v126, 0x3e38aa3b, v2
	v_exp_f32_e32 v126, v3
	s_waitcnt lgkmcnt(0)
	v_fmamk_f32 v3, v127, 0x3e38aa3b, v2
	v_exp_f32_e32 v127, v3
	v_fmamk_f32 v3, v128, 0x3e38aa3b, v2
	v_exp_f32_e32 v128, v3
	v_fmamk_f32 v3, v129, 0x3e38aa3b, v2
	v_mfma_f32_32x32x16_bf16 v[64:79], v[160:163], v[84:87], v[64:79]
	v_exp_f32_e32 v129, v3
	v_fmamk_f32 v3, v130, 0x3e38aa3b, v2
	v_exp_f32_e32 v130, v3
	v_fmamk_f32 v3, v131, 0x3e38aa3b, v2
	v_exp_f32_e32 v131, v3
	v_fmamk_f32 v3, v132, 0x3e38aa3b, v2
	ds_read_b64_tr_b16 v[96:97], v13 offset:8192
	ds_read_b64_tr_b16 v[98:99], v13 offset:10240
	ds_read_b64_tr_b16 v[100:101], v13 offset:8704
	ds_read_b64_tr_b16 v[102:103], v13 offset:10752
	ds_read_b64_tr_b16 v[104:105], v13 offset:9216
	ds_read_b64_tr_b16 v[106:107], v13 offset:11264
	ds_read_b64_tr_b16 v[108:109], v13 offset:9728
	ds_read_b64_tr_b16 v[110:111], v13 offset:11776
	v_exp_f32_e32 v132, v3
	v_fmamk_f32 v3, v133, 0x3e38aa3b, v2
	v_exp_f32_e32 v133, v3
	v_fmamk_f32 v3, v134, 0x3e38aa3b, v2
	v_exp_f32_e32 v134, v3
	v_fmamk_f32 v3, v135, 0x3e38aa3b, v2
	v_mfma_f32_32x32x16_bf16 v[48:63], v[182:185], v[84:87], v[48:63]
	v_exp_f32_e32 v135, v3
	v_fmamk_f32 v3, v136, 0x3e38aa3b, v2
	v_exp_f32_e32 v136, v3
	v_fmamk_f32 v3, v137, 0x3e38aa3b, v2
	v_exp_f32_e32 v137, v3
	v_mfma_f32_32x32x16_bf16 v[32:47], v[198:201], v[84:87], v[32:47]
	v_fmamk_f32 v3, v138, 0x3e38aa3b, v2
	v_exp_f32_e32 v138, v3
	v_fmamk_f32 v3, v139, 0x3e38aa3b, v2
	v_exp_f32_e32 v139, v3
	v_fmamk_f32 v3, v140, 0x3e38aa3b, v2
	v_exp_f32_e32 v140, v3
	v_mfma_f32_32x32x16_bf16 v[16:31], v[202:205], v[84:87], v[16:31]
	v_fmamk_f32 v3, v141, 0x3e38aa3b, v2
	v_exp_f32_e32 v141, v3
	v_fmamk_f32 v3, v142, 0x3e38aa3b, v2
	v_exp_f32_e32 v142, v3
	v_fmamk_f32 v3, v143, 0x3e38aa3b, v2
	s_waitcnt lgkmcnt(0)
	v_exp_f32_e32 v143, v3
	v_sub_f32_e32 v0, v193, v0
	v_mul_f32_e32 v0, 0x3e38aa3b, v0
	v_exp_f32_e32 v0, v0
	v_add_f32_e32 v2, 0, v112
	v_cndmask_b32_e64 v194, v0, 1.0, s[0:1]
	v_mfma_f32_32x32x16_bf16 v[64:79], v[96:99], v[88:91], v[64:79]
	v_mov_b32_e32 v193, v14
	v_add_f32_e32 v2, v113, v2
	v_add_f32_e32 v2, v114, v2
	v_add_f32_e32 v2, v115, v2
	v_add_f32_e32 v2, v116, v2
	ds_read_b64_tr_b16 v[160:161], v13 offset:12288
	ds_read_b64_tr_b16 v[162:163], v13 offset:14336
	ds_read_b64_tr_b16 v[182:183], v13 offset:12800
	ds_read_b64_tr_b16 v[184:185], v13 offset:14848
	ds_read_b64_tr_b16 v[198:199], v13 offset:13312
	ds_read_b64_tr_b16 v[200:201], v13 offset:15360
	ds_read_b64_tr_b16 v[202:203], v13 offset:13824
	ds_read_b64_tr_b16 v[204:205], v13 offset:15872
	v_add_f32_e32 v2, v117, v2
	v_add_f32_e32 v2, v118, v2
	v_add_f32_e32 v2, v119, v2
	v_add_f32_e32 v2, v120, v2
	v_add_f32_e32 v2, v121, v2
	v_add_f32_e32 v2, v122, v2
	v_mfma_f32_32x32x16_bf16 v[48:63], v[100:103], v[88:91], v[48:63]
	v_add_f32_e32 v2, v123, v2
	v_add_f32_e32 v2, v124, v2
	v_add_f32_e32 v2, v125, v2
	v_add_f32_e32 v2, v126, v2
	v_add_f32_e32 v2, v127, v2
	v_add_f32_e32 v2, v128, v2
	v_mfma_f32_32x32x16_bf16 v[32:47], v[104:107], v[88:91], v[32:47]
	v_add_f32_e32 v2, v129, v2
	v_add_f32_e32 v2, v130, v2
	v_add_f32_e32 v2, v131, v2
	v_add_f32_e32 v2, v132, v2
	v_add_f32_e32 v2, v133, v2
	v_mfma_f32_32x32x16_bf16 v[16:31], v[108:111], v[88:91], v[16:31]
	v_add_f32_e32 v2, v134, v2
	v_add_f32_e32 v2, v135, v2
	v_add_f32_e32 v2, v136, v2
	v_add_f32_e32 v2, v137, v2
	v_add_f32_e32 v2, v138, v2
	v_add_f32_e32 v2, v139, v2
	s_waitcnt lgkmcnt(0)
	v_add_f32_e32 v2, v140, v2
	v_add_f32_e32 v2, v141, v2
	v_add_f32_e32 v2, v142, v2
	v_add_f32_e32 v15, v143, v2
	v_mov_b32_e32 v195, v15
	v_mfma_f32_32x32x16_bf16 v[64:79], v[160:163], v[92:95], v[64:79]
	v_cvt_pk_bf16_f32 v112, v112, v113
	v_cvt_pk_bf16_f32 v113, v114, v115
	v_cvt_pk_bf16_f32 v114, v116, v117
	v_cvt_pk_bf16_f32 v115, v118, v119
	v_cvt_pk_bf16_f32 v116, v120, v121
	v_cvt_pk_bf16_f32 v117, v122, v123
	v_mfma_f32_32x32x16_bf16 v[48:63], v[182:185], v[92:95], v[48:63]
	v_cvt_pk_bf16_f32 v118, v124, v125
	v_cvt_pk_bf16_f32 v119, v126, v127
	v_cvt_pk_bf16_f32 v120, v128, v129
	v_cvt_pk_bf16_f32 v121, v130, v131
	v_cvt_pk_bf16_f32 v122, v132, v133
	v_mfma_f32_32x32x16_bf16 v[32:47], v[198:201], v[92:95], v[32:47]
	v_cvt_pk_bf16_f32 v123, v134, v135
	v_cvt_pk_bf16_f32 v124, v136, v137
	v_cvt_pk_bf16_f32 v125, v138, v139
	v_cvt_pk_bf16_f32 v126, v140, v141
	v_cvt_pk_bf16_f32 v127, v142, v143
	s_nop 1
	v_mfma_f32_32x32x16_bf16 v[16:31], v[202:205], v[92:95], v[16:31]
	v_permlane32_swap_b32_e32 v15, v195
	v_permlane32_swap_b32_e32 v112, v114
	v_permlane32_swap_b32_e32 v113, v115
	v_permlane32_swap_b32_e32 v116, v118
	v_permlane32_swap_b32_e32 v117, v119
	v_permlane32_swap_b32_e32 v120, v122
	v_permlane32_swap_b32_e32 v121, v123
	v_permlane32_swap_b32_e32 v124, v126
	v_permlane32_swap_b32_e32 v125, v127
	v_add_f32_e32 v15, v15, v195
	v_fmac_f32_e32 v15, v192, v194
	v_mov_b32_e32 v192, v15
.Lnl_qo:
	s_add_i32 s96, s11, 2
	s_cmp_lt_i32 s96, s8
	s_cbranch_scc0 .Lnl_noqo
		s_add_i32 s0, s10, 0x10000
		s_and_b32 s0, s0, 0x10000
		s_add_i32 s0, s0, 0
		v_add_u32_e32 v0, s0, v175
		ds_read_b128 v[2:5], v0 offset:0
		ds_read_b128 v[6:9], v0 offset:0x2000
		v_add_u32_e32 v0, s0, v176
		ds_read_b128 v[10:13], v0 offset:0
		ds_read_b128 v[160:163], v0 offset:0x2000
		s_waitcnt lgkmcnt(0)
		v_mfma_f32_32x32x16_bf16 v[80:95], v[2:5], v[144:147], 0
		v_add_u32_e32 v0, s0, v177
		ds_read_b128 v[2:5], v0 offset:0
		v_mfma_f32_32x32x16_bf16 v[96:111], v[6:9], v[144:147], 0
		ds_read_b128 v[6:9], v0 offset:0x2000
		v_add_u32_e32 v0, s0, v189
		v_mfma_f32_32x32x16_bf16 v[80:95], v[10:13], v[148:151], v[80:95]
		ds_read_b128 v[10:13], v0 offset:0
		ds_read_b128 v[182:185], v0 offset:0x2000
		s_waitcnt lgkmcnt(0)
		v_mfma_f32_32x32x16_bf16 v[96:111], v[160:163], v[148:151], v[96:111]
		v_mfma_f32_32x32x16_bf16 v[80:95], v[2:5], v[152:155], v[80:95]
		v_mfma_f32_32x32x16_bf16 v[96:111], v[6:9], v[152:155], v[96:111]
		v_mfma_f32_32x32x16_bf16 v[80:95], v[10:13], v[156:159], v[80:95]
		v_mfma_f32_32x32x16_bf16 v[96:111], v[182:185], v[156:159], v[96:111]
	s_nop 7
	s_nop 3
.Lnl_noqo:
	s_add_i32 s11, s11, 2
	s_add_i32 s10, s10, 0x10000
	s_add_u32 s78, s78, 0xc0000
	s_addc_u32 s79, s79, 0
	s_cmp_lt_i32 s11, s9
	s_cbranch_scc1 .LBB0_588
	s_cmp_lt_i32 s8, s9
	s_cbranch_scc1 .Lnl_done
	v_cmp_gt_f32_e32 vcc, 1.0, v194
	s_cbranch_vccz .Lnl_nors_dr
	v_pk_mul_f32 v[78:79], v[78:79], v[194:195] op_sel_hi:[1,0]
	v_pk_mul_f32 v[76:77], v[76:77], v[194:195] op_sel_hi:[1,0]
	v_pk_mul_f32 v[74:75], v[74:75], v[194:195] op_sel_hi:[1,0]
	v_pk_mul_f32 v[72:73], v[72:73], v[194:195] op_sel_hi:[1,0]
	v_pk_mul_f32 v[70:71], v[70:71], v[194:195] op_sel_hi:[1,0]
	v_pk_mul_f32 v[68:69], v[68:69], v[194:195] op_sel_hi:[1,0]
	v_pk_mul_f32 v[66:67], v[66:67], v[194:195] op_sel_hi:[1,0]
	v_pk_mul_f32 v[64:65], v[64:65], v[194:195] op_sel_hi:[1,0]
	v_pk_mul_f32 v[62:63], v[62:63], v[194:195] op_sel_hi:[1,0]
	v_pk_mul_f32 v[60:61], v[60:61], v[194:195] op_sel_hi:[1,0]
	v_pk_mul_f32 v[58:59], v[58:59], v[194:195] op_sel_hi:[1,0]
	v_pk_mul_f32 v[56:57], v[56:57], v[194:195] op_sel_hi:[1,0]
	v_pk_mul_f32 v[54:55], v[54:55], v[194:195] op_sel_hi:[1,0]
	v_pk_mul_f32 v[52:53], v[52:53], v[194:195] op_sel_hi:[1,0]
	v_pk_mul_f32 v[50:51], v[50:51], v[194:195] op_sel_hi:[1,0]
	v_pk_mul_f32 v[48:49], v[48:49], v[194:195] op_sel_hi:[1,0]
	v_pk_mul_f32 v[46:47], v[46:47], v[194:195] op_sel_hi:[1,0]
	v_pk_mul_f32 v[44:45], v[44:45], v[194:195] op_sel_hi:[1,0]
	v_pk_mul_f32 v[42:43], v[42:43], v[194:195] op_sel_hi:[1,0]
	v_pk_mul_f32 v[40:41], v[40:41], v[194:195] op_sel_hi:[1,0]
	v_pk_mul_f32 v[38:39], v[38:39], v[194:195] op_sel_hi:[1,0]
	v_pk_mul_f32 v[36:37], v[36:37], v[194:195] op_sel_hi:[1,0]
	v_pk_mul_f32 v[34:35], v[34:35], v[194:195] op_sel_hi:[1,0]
	v_pk_mul_f32 v[32:33], v[32:33], v[194:195] op_sel_hi:[1,0]
	v_pk_mul_f32 v[30:31], v[30:31], v[194:195] op_sel_hi:[1,0]
	v_pk_mul_f32 v[28:29], v[28:29], v[194:195] op_sel_hi:[1,0]
	v_pk_mul_f32 v[26:27], v[26:27], v[194:195] op_sel_hi:[1,0]
	v_pk_mul_f32 v[24:25], v[24:25], v[194:195] op_sel_hi:[1,0]
	v_pk_mul_f32 v[22:23], v[22:23], v[194:195] op_sel_hi:[1,0]
	v_pk_mul_f32 v[20:21], v[20:21], v[194:195] op_sel_hi:[1,0]
	v_pk_mul_f32 v[18:19], v[18:19], v[194:195] op_sel_hi:[1,0]
	v_pk_mul_f32 v[16:17], v[16:17], v[194:195] op_sel_hi:[1,0]
.Lnl_nors_dr:
	s_add_i32 s0, s10, 0x18000
	s_and_b32 s0, s0, 0x18000
	v_add_u32_e32 v13, s0, v191
	ds_read_b64_tr_b16 v[96:97], v13 offset:0
	ds_read_b64_tr_b16 v[98:99], v13 offset:2048
	ds_read_b64_tr_b16 v[100:101], v13 offset:512
	ds_read_b64_tr_b16 v[102:103], v13 offset:2560
	ds_read_b64_tr_b16 v[104:105], v13 offset:1024
	ds_read_b64_tr_b16 v[106:107], v13 offset:3072
	ds_read_b64_tr_b16 v[108:109], v13 offset:1536
	ds_read_b64_tr_b16 v[110:111], v13 offset:3584
	s_waitcnt lgkmcnt(0)
	v_mfma_f32_32x32x16_bf16 v[64:79], v[96:99], v[112:115], v[64:79]
	ds_read_b64_tr_b16 v[160:161], v13 offset:4096
	ds_read_b64_tr_b16 v[162:163], v13 offset:6144
	ds_read_b64_tr_b16 v[182:183], v13 offset:4608
	ds_read_b64_tr_b16 v[184:185], v13 offset:6656
	ds_read_b64_tr_b16 v[198:199], v13 offset:5120
	ds_read_b64_tr_b16 v[200:201], v13 offset:7168
	ds_read_b64_tr_b16 v[202:203], v13 offset:5632
	ds_read_b64_tr_b16 v[204:205], v13 offset:7680
	v_mfma_f32_32x32x16_bf16 v[48:63], v[100:103], v[112:115], v[48:63]
	v_mfma_f32_32x32x16_bf16 v[32:47], v[104:107], v[112:115], v[32:47]
	v_mfma_f32_32x32x16_bf16 v[16:31], v[108:111], v[112:115], v[16:31]
	s_waitcnt lgkmcnt(0)
	v_mfma_f32_32x32x16_bf16 v[64:79], v[160:163], v[116:119], v[64:79]
	ds_read_b64_tr_b16 v[96:97], v13 offset:8192
	ds_read_b64_tr_b16 v[98:99], v13 offset:10240
	ds_read_b64_tr_b16 v[100:101], v13 offset:8704
	ds_read_b64_tr_b16 v[102:103], v13 offset:10752
	ds_read_b64_tr_b16 v[104:105], v13 offset:9216
	ds_read_b64_tr_b16 v[106:107], v13 offset:11264
	ds_read_b64_tr_b16 v[108:109], v13 offset:9728
	ds_read_b64_tr_b16 v[110:111], v13 offset:11776
	v_mfma_f32_32x32x16_bf16 v[48:63], v[182:185], v[116:119], v[48:63]
	v_mfma_f32_32x32x16_bf16 v[32:47], v[198:201], v[116:119], v[32:47]
	v_mfma_f32_32x32x16_bf16 v[16:31], v[202:205], v[116:119], v[16:31]
	s_waitcnt lgkmcnt(0)
	v_mfma_f32_32x32x16_bf16 v[64:79], v[96:99], v[120:123], v[64:79]
	ds_read_b64_tr_b16 v[160:161], v13 offset:12288
	ds_read_b64_tr_b16 v[162:163], v13 offset:14336
	ds_read_b64_tr_b16 v[182:183], v13 offset:12800
	ds_read_b64_tr_b16 v[184:185], v13 offset:14848
	ds_read_b64_tr_b16 v[198:199], v13 offset:13312
	ds_read_b64_tr_b16 v[200:201], v13 offset:15360
	ds_read_b64_tr_b16 v[202:203], v13 offset:13824
	ds_read_b64_tr_b16 v[204:205], v13 offset:15872
	v_mfma_f32_32x32x16_bf16 v[48:63], v[100:103], v[120:123], v[48:63]
	v_mfma_f32_32x32x16_bf16 v[32:47], v[104:107], v[120:123], v[32:47]
	v_mfma_f32_32x32x16_bf16 v[16:31], v[108:111], v[120:123], v[16:31]
	s_waitcnt lgkmcnt(0)
	v_mfma_f32_32x32x16_bf16 v[64:79], v[160:163], v[124:127], v[64:79]
	v_mfma_f32_32x32x16_bf16 v[48:63], v[182:185], v[124:127], v[48:63]
	v_mfma_f32_32x32x16_bf16 v[32:47], v[198:201], v[124:127], v[32:47]
	v_mfma_f32_32x32x16_bf16 v[16:31], v[202:205], v[124:127], v[16:31]
.Lnl_done:
	s_nop 7
	s_nop 7
